# attention online softmax: running max only updated when it grows by more than 8 (log2), so the O rescale is rarely executed; exact by shift invariance
# speedup vs baseline: 1.0133x; 1.0127x over previous
.LBB0_1738:
	s_nop 4
	v_max3_f32 v183, v80, v81, v82
	v_max3_f32 v184, v88, v89, v90
	v_max3_f32 v183, v183, v83, v84
	v_max3_f32 v184, v184, v91, v92
	v_max3_f32 v183, v183, v85, v86
	v_max3_f32 v184, v184, v93, v94
	v_max_f32_e32 v183, v183, v87
	v_max_f32_e32 v184, v184, v95
	v_max3_f32 v181, v64, v65, v66
	v_max3_f32 v182, v72, v73, v74
	v_max3_f32 v181, v181, v67, v68
	v_max3_f32 v182, v182, v75, v76
	v_max3_f32 v181, v181, v69, v70
	v_max3_f32 v182, v182, v77, v78
	v_max_f32_e32 v181, v181, v71
	v_max_f32_e32 v182, v182, v79
	v_max3_f32 v181, v181, v182, v183
	v_max_f32_e32 v181, v181, v184
	s_or_b64 s[0:1], s[8:9], s[0:1]
	v_cndmask_b32_e64 v181, v159, v181, s[0:1]
	ds_bpermute_b32 v182, v169, v181
	s_waitcnt lgkmcnt(0)
	v_max3_f32 v181, v154, v181, v182
	v_sub_f32_e32 v182, v181, v154
	v_cmp_lt_f32_e32 vcc, 0x41000000, v182
	s_nop 1
	v_cndmask_b32_e32 v181, v154, v181, vcc
	v_sub_f32_e32 v154, v154, v181
	v_exp_f32_e32 v154, v154
	s_nop 0
	v_cmp_neq_f32_e32 vcc, 1.0, v154
	s_cbranch_vccz .LBB0_1727
	v_pk_mul_f32 v[62:63], v[62:63], v[154:155] op_sel_hi:[1,0]
	v_pk_mul_f32 v[60:61], v[60:61], v[154:155] op_sel_hi:[1,0]
	v_pk_mul_f32 v[58:59], v[58:59], v[154:155] op_sel_hi:[1,0]
	v_pk_mul_f32 v[56:57], v[56:57], v[154:155] op_sel_hi:[1,0]
	v_pk_mul_f32 v[54:55], v[54:55], v[154:155] op_sel_hi:[1,0]
	v_pk_mul_f32 v[52:53], v[52:53], v[154:155] op_sel_hi:[1,0]
	v_pk_mul_f32 v[50:51], v[50:51], v[154:155] op_sel_hi:[1,0]
	v_pk_mul_f32 v[48:49], v[48:49], v[154:155] op_sel_hi:[1,0]
	v_pk_mul_f32 v[46:47], v[46:47], v[154:155] op_sel_hi:[1,0]
	v_pk_mul_f32 v[44:45], v[44:45], v[154:155] op_sel_hi:[1,0]
	v_pk_mul_f32 v[42:43], v[42:43], v[154:155] op_sel_hi:[1,0]
	v_pk_mul_f32 v[40:41], v[40:41], v[154:155] op_sel_hi:[1,0]
	v_pk_mul_f32 v[38:39], v[38:39], v[154:155] op_sel_hi:[1,0]
	v_pk_mul_f32 v[36:37], v[36:37], v[154:155] op_sel_hi:[1,0]
	v_pk_mul_f32 v[34:35], v[34:35], v[154:155] op_sel_hi:[1,0]
	v_pk_mul_f32 v[32:33], v[32:33], v[154:155] op_sel_hi:[1,0]
	v_pk_mul_f32 v[30:31], v[30:31], v[154:155] op_sel_hi:[1,0]
	v_pk_mul_f32 v[28:29], v[28:29], v[154:155] op_sel_hi:[1,0]
	v_pk_mul_f32 v[26:27], v[26:27], v[154:155] op_sel_hi:[1,0]
	v_pk_mul_f32 v[24:25], v[24:25], v[154:155] op_sel_hi:[1,0]
	v_pk_mul_f32 v[22:23], v[22:23], v[154:155] op_sel_hi:[1,0]
	v_pk_mul_f32 v[20:21], v[20:21], v[154:155] op_sel_hi:[1,0]
	v_pk_mul_f32 v[18:19], v[18:19], v[154:155] op_sel_hi:[1,0]
	v_pk_mul_f32 v[16:17], v[16:17], v[154:155] op_sel_hi:[1,0]
	v_pk_mul_f32 v[14:15], v[14:15], v[154:155] op_sel_hi:[1,0]
	v_pk_mul_f32 v[12:13], v[12:13], v[154:155] op_sel_hi:[1,0]
	v_pk_mul_f32 v[10:11], v[10:11], v[154:155] op_sel_hi:[1,0]
	v_pk_mul_f32 v[8:9], v[8:9], v[154:155] op_sel_hi:[1,0]
	v_pk_mul_f32 v[6:7], v[6:7], v[154:155] op_sel_hi:[1,0]
	v_pk_mul_f32 v[4:5], v[4:5], v[154:155] op_sel_hi:[1,0]
	v_pk_mul_f32 v[2:3], v[2:3], v[154:155] op_sel_hi:[1,0]
	v_pk_mul_f32 v[0:1], v[0:1], v[154:155] op_sel_hi:[1,0]
	s_branch .LBB0_1727

.LBB0_1749:
	s_nop 4
	v_max3_f32 v98, v80, v81, v82
	v_max3_f32 v99, v88, v89, v90
	v_max3_f32 v98, v98, v83, v84
	v_max3_f32 v99, v99, v91, v92
	v_max3_f32 v98, v98, v85, v86
	v_max3_f32 v99, v99, v93, v94
	v_max_f32_e32 v98, v98, v87
	v_max_f32_e32 v99, v99, v95
	v_max3_f32 v96, v64, v65, v66
	v_max3_f32 v97, v72, v73, v74
	v_max3_f32 v96, v96, v67, v68
	v_max3_f32 v97, v97, v75, v76
	v_max3_f32 v96, v96, v69, v70
	v_max3_f32 v97, v97, v77, v78
	v_max_f32_e32 v96, v96, v71
	v_max_f32_e32 v97, v97, v79
	v_max3_f32 v96, v96, v97, v98
	v_max_f32_e32 v96, v96, v99
	s_or_b64 s[0:1], s[8:9], s[0:1]
	v_cndmask_b32_e64 v96, v159, v96, s[0:1]
	ds_bpermute_b32 v97, v169, v96
	s_waitcnt lgkmcnt(0)
	v_max3_f32 v97, v154, v96, v97
	v_sub_f32_e32 v96, v97, v154
	v_cmp_lt_f32_e32 vcc, 0x41000000, v96
	s_nop 1
	v_cndmask_b32_e32 v97, v154, v97, vcc
	v_sub_f32_e32 v96, v154, v97
	v_exp_f32_e32 v96, v96
	s_nop 0
	v_cmp_neq_f32_e32 vcc, 1.0, v96
	s_cbranch_vccz .LBB0_1751
	v_pk_mul_f32 v[62:63], v[62:63], v[96:97] op_sel_hi:[1,0]
	v_pk_mul_f32 v[60:61], v[60:61], v[96:97] op_sel_hi:[1,0]
	v_pk_mul_f32 v[58:59], v[58:59], v[96:97] op_sel_hi:[1,0]
	v_pk_mul_f32 v[56:57], v[56:57], v[96:97] op_sel_hi:[1,0]
	v_pk_mul_f32 v[54:55], v[54:55], v[96:97] op_sel_hi:[1,0]
	v_pk_mul_f32 v[52:53], v[52:53], v[96:97] op_sel_hi:[1,0]
	v_pk_mul_f32 v[50:51], v[50:51], v[96:97] op_sel_hi:[1,0]
	v_pk_mul_f32 v[48:49], v[48:49], v[96:97] op_sel_hi:[1,0]
	v_pk_mul_f32 v[46:47], v[46:47], v[96:97] op_sel_hi:[1,0]
	v_pk_mul_f32 v[44:45], v[44:45], v[96:97] op_sel_hi:[1,0]
	v_pk_mul_f32 v[42:43], v[42:43], v[96:97] op_sel_hi:[1,0]
	v_pk_mul_f32 v[40:41], v[40:41], v[96:97] op_sel_hi:[1,0]
	v_pk_mul_f32 v[38:39], v[38:39], v[96:97] op_sel_hi:[1,0]
	v_pk_mul_f32 v[36:37], v[36:37], v[96:97] op_sel_hi:[1,0]
	v_pk_mul_f32 v[34:35], v[34:35], v[96:97] op_sel_hi:[1,0]
	v_pk_mul_f32 v[32:33], v[32:33], v[96:97] op_sel_hi:[1,0]
	v_pk_mul_f32 v[30:31], v[30:31], v[96:97] op_sel_hi:[1,0]
	v_pk_mul_f32 v[28:29], v[28:29], v[96:97] op_sel_hi:[1,0]
	v_pk_mul_f32 v[26:27], v[26:27], v[96:97] op_sel_hi:[1,0]
	v_pk_mul_f32 v[24:25], v[24:25], v[96:97] op_sel_hi:[1,0]
	v_pk_mul_f32 v[22:23], v[22:23], v[96:97] op_sel_hi:[1,0]
	v_pk_mul_f32 v[20:21], v[20:21], v[96:97] op_sel_hi:[1,0]
	v_pk_mul_f32 v[18:19], v[18:19], v[96:97] op_sel_hi:[1,0]
	v_pk_mul_f32 v[16:17], v[16:17], v[96:97] op_sel_hi:[1,0]
	v_pk_mul_f32 v[14:15], v[14:15], v[96:97] op_sel_hi:[1,0]
	v_pk_mul_f32 v[12:13], v[12:13], v[96:97] op_sel_hi:[1,0]
	v_pk_mul_f32 v[10:11], v[10:11], v[96:97] op_sel_hi:[1,0]
	v_pk_mul_f32 v[8:9], v[8:9], v[96:97] op_sel_hi:[1,0]
	v_pk_mul_f32 v[6:7], v[6:7], v[96:97] op_sel_hi:[1,0]
	v_pk_mul_f32 v[4:5], v[4:5], v[96:97] op_sel_hi:[1,0]
	v_pk_mul_f32 v[2:3], v[2:3], v[96:97] op_sel_hi:[1,0]
	v_pk_mul_f32 v[0:1], v[0:1], v[96:97] op_sel_hi:[1,0]

.LBB0_1792:
	s_nop 4
	v_max3_f32 v98, v80, v81, v82
	v_max3_f32 v99, v88, v89, v90
	v_max3_f32 v98, v98, v83, v84
	v_max3_f32 v99, v99, v91, v92
	v_max3_f32 v98, v98, v85, v86
	v_max3_f32 v99, v99, v93, v94
	v_max_f32_e32 v98, v98, v87
	v_max_f32_e32 v99, v99, v95
	v_max3_f32 v96, v64, v65, v66
	v_max3_f32 v97, v72, v73, v74
	v_max3_f32 v96, v96, v67, v68
	v_max3_f32 v97, v97, v75, v76
	v_max3_f32 v96, v96, v69, v70
	v_max3_f32 v97, v97, v77, v78
	v_max_f32_e32 v96, v96, v71
	v_max_f32_e32 v97, v97, v79
	v_max3_f32 v96, v96, v97, v98
	v_max_f32_e32 v96, v96, v99
	s_or_b64 s[0:1], s[8:9], s[0:1]
	v_cndmask_b32_e64 v96, v159, v96, s[0:1]
	ds_bpermute_b32 v97, v169, v96
	s_waitcnt lgkmcnt(0)
	v_max3_f32 v97, v154, v96, v97
	v_sub_f32_e32 v96, v97, v154
	v_cmp_lt_f32_e32 vcc, 0x41000000, v96
	s_nop 1
	v_cndmask_b32_e32 v97, v154, v97, vcc
	v_sub_f32_e32 v96, v154, v97
	v_exp_f32_e32 v96, v96
	s_nop 0
	v_cmp_neq_f32_e32 vcc, 1.0, v96
	s_cbranch_vccz .LBB0_1710
	v_pk_mul_f32 v[62:63], v[62:63], v[96:97] op_sel_hi:[1,0]
	v_pk_mul_f32 v[60:61], v[60:61], v[96:97] op_sel_hi:[1,0]
	v_pk_mul_f32 v[58:59], v[58:59], v[96:97] op_sel_hi:[1,0]
	v_pk_mul_f32 v[56:57], v[56:57], v[96:97] op_sel_hi:[1,0]
	v_pk_mul_f32 v[54:55], v[54:55], v[96:97] op_sel_hi:[1,0]
	v_pk_mul_f32 v[52:53], v[52:53], v[96:97] op_sel_hi:[1,0]
	v_pk_mul_f32 v[50:51], v[50:51], v[96:97] op_sel_hi:[1,0]
	v_pk_mul_f32 v[48:49], v[48:49], v[96:97] op_sel_hi:[1,0]
	v_pk_mul_f32 v[46:47], v[46:47], v[96:97] op_sel_hi:[1,0]
	v_pk_mul_f32 v[44:45], v[44:45], v[96:97] op_sel_hi:[1,0]
	v_pk_mul_f32 v[42:43], v[42:43], v[96:97] op_sel_hi:[1,0]
	v_pk_mul_f32 v[40:41], v[40:41], v[96:97] op_sel_hi:[1,0]
	v_pk_mul_f32 v[38:39], v[38:39], v[96:97] op_sel_hi:[1,0]
	v_pk_mul_f32 v[36:37], v[36:37], v[96:97] op_sel_hi:[1,0]
	v_pk_mul_f32 v[34:35], v[34:35], v[96:97] op_sel_hi:[1,0]
	v_pk_mul_f32 v[32:33], v[32:33], v[96:97] op_sel_hi:[1,0]
	v_pk_mul_f32 v[30:31], v[30:31], v[96:97] op_sel_hi:[1,0]
	v_pk_mul_f32 v[28:29], v[28:29], v[96:97] op_sel_hi:[1,0]
	v_pk_mul_f32 v[26:27], v[26:27], v[96:97] op_sel_hi:[1,0]
	v_pk_mul_f32 v[24:25], v[24:25], v[96:97] op_sel_hi:[1,0]
	v_pk_mul_f32 v[22:23], v[22:23], v[96:97] op_sel_hi:[1,0]
	v_pk_mul_f32 v[20:21], v[20:21], v[96:97] op_sel_hi:[1,0]
	v_pk_mul_f32 v[18:19], v[18:19], v[96:97] op_sel_hi:[1,0]
	v_pk_mul_f32 v[16:17], v[16:17], v[96:97] op_sel_hi:[1,0]
	v_pk_mul_f32 v[14:15], v[14:15], v[96:97] op_sel_hi:[1,0]
	v_pk_mul_f32 v[12:13], v[12:13], v[96:97] op_sel_hi:[1,0]
	v_pk_mul_f32 v[10:11], v[10:11], v[96:97] op_sel_hi:[1,0]
	v_pk_mul_f32 v[8:9], v[8:9], v[96:97] op_sel_hi:[1,0]
	v_pk_mul_f32 v[6:7], v[6:7], v[96:97] op_sel_hi:[1,0]
	v_pk_mul_f32 v[4:5], v[4:5], v[96:97] op_sel_hi:[1,0]
	v_pk_mul_f32 v[2:3], v[2:3], v[96:97] op_sel_hi:[1,0]
	v_pk_mul_f32 v[0:1], v[0:1], v[96:97] op_sel_hi:[1,0]
	s_branch .LBB0_1710
